# attn pair loop: deep LDS prefetch + permlane max; E4/O5 XCD-local tile map
# speedup vs baseline: 1.0309x; 1.0309x over previous
; DI int get_bid() { int b = blockIdx.x; asm volatile("" : "+s"(b)); return b; }
; DI void phase_even(const Params& p, int e, int sub, char* smem) {
;     ...
;     for (int t = get_bid(); t < 512 + 64; t += gridDim.x) {
;       if (t < 512) {
;         const int tm = t >> 3, tn = t & 7;
;         gemm_dma<256>(gbuf + (size_t)tm * 256 * 2048, 2048, W + WE_OUT + (size_t)tn * 128 * 2048, 2048, 2048, smem, tm * 256, tn * 128, epi);
;       } else {
;         const int u = t - 512, tm = u >> 3, tn = u & 7, m0 = M_PROMPT + tm * 64;
;         gemm_tile<2>(gbuf + (size_t)m0 * 2048, 2048, W + WE_OUT + (size_t)tn * 128 * 2048, 2048, 2048, smem, m0, tn * 128, epi);
;       }
;     }
.LBB0_21:
	s_andn2_b64 vcc, exec, s[38:39]
	s_cbranch_vccnz .LBB0_36
	s_mov_b32 s4, s2
	v_readlane_b32 s98, v255, 11
	s_nop 0
	s_cmp_lg_u32 s98, 0x200
	s_cbranch_scc1 .Lxmap_skip0
	s_and_b32 s98, s4, 7
	s_lshl_b32 s98, s98, 6
	s_bfe_u32 s99, s4, 0x30006
	s_lshl_b32 s99, s99, 3
	s_or_b32 s98, s98, s99
	s_bfe_u32 s99, s4, 0x30003
	s_or_b32 s4, s98, s99
.Lxmap_skip0:
	s_cmpk_gt_i32 s4, 0x23f
	s_cbranch_scc1 .LBB0_36
	s_lshl_b32 s5, s4, 3
	s_mov_b32 s6, s4
	s_branch .LBB0_26

; DI int get_bid() { int b = blockIdx.x; asm volatile("" : "+s"(b)); return b; }
; DI void phase_even(const Params& p, int e, int sub, char* smem) {
;     ...
;     for (int t = get_bid(); t < 512 + 64; t += gridDim.x) {
;       if (t < 512) {
;         const int tm = t >> 3, tn = t & 7;
;         gemm_dma<256>(gbuf + (size_t)tm * 256 * 2048, 2048, W + WE_OUT + (size_t)tn * 128 * 2048, 2048, 2048, smem, tm * 256, tn * 128, epi);
;       } else {
;         const int u = t - 512, tm = u >> 3, tn = u & 7, m0 = M_PROMPT + tm * 64;
;         gemm_tile<2>(gbuf + (size_t)m0 * 2048, 2048, W + WE_OUT + (size_t)tn * 128 * 2048, 2048, 2048, smem, m0, tn * 128, epi);
;       }
;     }
.LBB0_25:
	v_readlane_b32 s8, v255, 5
	v_readlane_b32 s14, v255, 11
	v_readlane_b32 s7, v254, 56
	s_cmp_lg_u32 s14, 0x200
	s_cbranch_scc1 .Lxmap_lskip0
	s_cmpk_gt_i32 s6, 0x1ff
	s_cbranch_scc1 .Lxmap_lskip0
	s_mov_b32 s4, s2
	s_mov_b32 s6, s2
	s_lshl_b32 s5, s2, 3
.Lxmap_lskip0:
	s_add_i32 s6, s6, s14
	s_add_i32 s4, s4, s14
	s_add_i32 s5, s5, s7
	s_cmpk_gt_i32 s6, 0x23f
	v_readlane_b32 s9, v255, 6
	v_readlane_b32 s10, v255, 7
	v_readlane_b32 s11, v255, 8
	v_readlane_b32 s12, v255, 9
	v_readlane_b32 s13, v255, 10
	v_readlane_b32 s15, v255, 12
	s_cbranch_scc1 .LBB0_36

; DI void attn_item(const u16* __restrict__ qbuf, const u16* __restrict__ knope, const u16* __restrict__ krope, ...
;     ...
;   __syncthreads();
;   ATT_DMA(0u)
;   for (int kt = 0; kt < ntiles; ++kt) {
;     asm volatile("s_waitcnt vmcnt(0)" ::: "memory");
;     __syncthreads();
;     if (kt + 1 < ntiles) ATT_DMA((unsigned)((kt + 1) & 1) * 40960u)
;     if (active && kt < my_tiles) {
;       const char* cur = smem + (kt & 1) * 40960;
;       f32x16 st[2];
; #pragma unroll
;       for (int mt = 0; mt < 2; ++mt) {
; #pragma unroll
;         for (int j = 0; j < 16; ++j) st[mt][j] = 0.f;
; #pragma unroll
;         for (int ks = 0; ks < 12; ++ks) {
;           const bf16x8 kf = *(const bf16x8*)(cur + koff[ks & 3] + (ks >> 2) * 8192 + mt * 4096);
;           st[mt] = __builtin_amdgcn_mfma_f32_32x32x16_bf16(kf, qf[ks], st[mt], 0, 0, 0);
;         }
;       }
.LBB0_46:
	s_add_i32 s10, s11, 1
	s_bitcmp1_b32 s10, 0
	v_add_u32_e32 v66, v152, v154
	s_cselect_b32 s12, 0xa000, 0
	v_add_u32_e32 v182, 0x1010000, v66
	v_add_u32_e32 v67, v153, v154
	s_waitcnt vmcnt(0)
	s_barrier
	s_add_i32 s13, s12, s7
	v_lshl_add_u64 v[64:65], v[182:183], 1, s[92:93]
	s_mov_b32 s14, m0
	s_mov_b32 m0, s13
	s_nop 0
	global_load_lds_dwordx4 v[64:65], off
	s_mov_b32 m0, s14
	v_add_u32_e32 v182, 0x1012000, v67
	v_lshl_add_u64 v[64:65], v[182:183], 1, s[92:93]
	s_add_i32 s14, s13, 0x400
	s_mov_b32 s15, m0
	s_mov_b32 m0, s14
	s_nop 0
	global_load_lds_dwordx4 v[64:65], off
	s_mov_b32 m0, s15
	v_add_u32_e32 v182, 0x1014000, v66
	v_lshl_add_u64 v[64:65], v[182:183], 1, s[92:93]
	s_add_i32 s14, s13, 0x800
	s_mov_b32 s15, m0
	s_mov_b32 m0, s14
	s_nop 0
	global_load_lds_dwordx4 v[64:65], off
	s_mov_b32 m0, s15
	v_add_u32_e32 v182, 0x1016000, v67
	s_mov_b32 s2, 0x101000
	v_lshl_add_u64 v[64:65], v[182:183], 1, s[92:93]
	s_addk_i32 s13, 0xc00
	s_mov_b32 s14, m0
	s_mov_b32 m0, s13
	s_nop 0
	global_load_lds_dwordx4 v[64:65], off
	s_mov_b32 m0, s14
	v_add3_u32 v182, v152, v155, s2
	s_mov_b32 s2, 0x101200
	s_add_i32 s13, s12, s8
	v_lshl_add_u64 v[64:65], v[182:183], 1, s[30:31]
	s_mov_b32 s14, m0
	s_mov_b32 m0, s13
	s_nop 0
	global_load_lds_dwordx4 v[64:65], off
	s_mov_b32 m0, s14
	v_add3_u32 v182, v153, v155, s2
	v_add_u32_e32 v66, v152, v156
	v_lshl_add_u64 v[64:65], v[182:183], 1, s[30:31]
	s_addk_i32 s13, 0x400
	s_mov_b32 s14, m0
	s_mov_b32 m0, s13
	s_nop 0
	global_load_lds_dwordx4 v[64:65], off
	s_mov_b32 m0, s14
	v_add_u32_e32 v182, 64, v66
	v_add_u32_e32 v67, v153, v156
	s_add_i32 s12, s12, s9
	v_lshl_add_u64 v[64:65], v[182:183], 1, s[40:41]
	s_mov_b32 s13, m0
	s_mov_b32 m0, s12
	s_nop 0
	global_load_lds_dwordx4 v[64:65], off
	s_mov_b32 m0, s13
	v_add_u32_e32 v182, 0x2440, v67
	v_lshl_add_u64 v[64:65], v[182:183], 1, s[40:41]
	s_add_i32 s13, s12, 0x400
	s_mov_b32 s14, m0
	s_mov_b32 m0, s13
	s_nop 0
	global_load_lds_dwordx4 v[64:65], off
	s_mov_b32 m0, s14
	v_add_u32_e32 v182, 0x4840, v66
	v_lshl_add_u64 v[64:65], v[182:183], 1, s[40:41]
	s_add_i32 s13, s12, 0x800
	s_mov_b32 s14, m0
	s_mov_b32 m0, s13
	s_nop 0
	global_load_lds_dwordx4 v[64:65], off
	s_mov_b32 m0, s14
	v_add_u32_e32 v182, 0x6c40, v67
	v_lshl_add_u64 v[64:65], v[182:183], 1, s[40:41]
	s_addk_i32 s12, 0xc00
	s_mov_b32 s13, m0
	s_mov_b32 m0, s12
	s_nop 0
	global_load_lds_dwordx4 v[64:65], off
	s_mov_b32 m0, s13
	s_and_saveexec_b64 s[42:43], s[38:39]
	s_cbranch_execz .LBB0_50
	s_bitcmp1_b32 s11, 0
	s_cselect_b32 s11, 0xa000, 0
	v_or_b32_e32 v157, s11, v150
	ds_read_b128 v[64:67], v157
	v_or_b32_e32 v162, s11, v149
	ds_read_b128 v[80:83], v162
	v_or_b32_e32 v163, s11, v148
	v_or_b32_e32 v164, s11, v145
	v_cmp_lt_i32_e32 vcc, v206, v205
	s_waitcnt lgkmcnt(1)
	v_mfma_f32_32x32x16_bf16 v[64:79], v[64:67], v[140:143], 0
	ds_read_b128 v[158:161], v162 offset:4096
	s_waitcnt lgkmcnt(1)
	v_mfma_f32_32x32x16_bf16 v[64:79], v[80:83], v[136:139], v[64:79]
	ds_read_b128 v[80:83], v163
	s_waitcnt lgkmcnt(0)
	v_mfma_f32_32x32x16_bf16 v[64:79], v[80:83], v[132:135], v[64:79]
	ds_read_b128 v[80:83], v164
	s_waitcnt lgkmcnt(0)
	v_mfma_f32_32x32x16_bf16 v[64:79], v[80:83], v[128:131], v[64:79]
	ds_read_b128 v[80:83], v157 offset:8192
	s_waitcnt lgkmcnt(0)
	v_mfma_f32_32x32x16_bf16 v[64:79], v[80:83], v[124:127], v[64:79]
	ds_read_b128 v[80:83], v162 offset:8192
	s_waitcnt lgkmcnt(0)
	v_mfma_f32_32x32x16_bf16 v[64:79], v[80:83], v[120:123], v[64:79]
	ds_read_b128 v[80:83], v163 offset:8192
	s_waitcnt lgkmcnt(0)
	v_mfma_f32_32x32x16_bf16 v[64:79], v[80:83], v[116:119], v[64:79]
	ds_read_b128 v[80:83], v164 offset:8192
	s_waitcnt lgkmcnt(0)
	v_mfma_f32_32x32x16_bf16 v[64:79], v[80:83], v[112:115], v[64:79]
	ds_read_b128 v[80:83], v157 offset:16384
	s_waitcnt lgkmcnt(0)
	v_mfma_f32_32x32x16_bf16 v[64:79], v[80:83], v[108:111], v[64:79]
	ds_read_b128 v[80:83], v162 offset:16384
	s_waitcnt lgkmcnt(0)
	v_mfma_f32_32x32x16_bf16 v[64:79], v[80:83], v[104:107], v[64:79]
	ds_read_b128 v[80:83], v163 offset:16384
	s_waitcnt lgkmcnt(0)
	v_mfma_f32_32x32x16_bf16 v[64:79], v[80:83], v[100:103], v[64:79]
	ds_read_b128 v[80:83], v164 offset:16384
	s_waitcnt lgkmcnt(0)
	v_mfma_f32_32x32x16_bf16 v[64:79], v[80:83], v[96:99], v[64:79]
	ds_read_b128 v[80:83], v157 offset:4096
	s_waitcnt lgkmcnt(0)
	v_mfma_f32_32x32x16_bf16 v[80:95], v[80:83], v[140:143], 0
	v_mfma_f32_32x32x16_bf16 v[80:95], v[158:161], v[136:139], v[80:95]
	ds_read_b128 v[158:161], v163 offset:4096
	s_waitcnt lgkmcnt(0)
	v_mfma_f32_32x32x16_bf16 v[80:95], v[158:161], v[132:135], v[80:95]
	ds_read_b128 v[158:161], v164 offset:4096
	s_waitcnt lgkmcnt(0)
	v_mfma_f32_32x32x16_bf16 v[80:95], v[158:161], v[128:131], v[80:95]
	ds_read_b128 v[158:161], v157 offset:12288
	s_waitcnt lgkmcnt(0)
; DI void attn_item(const u16* __restrict__ qbuf, const u16* __restrict__ knope, const u16* __restrict__ krope, ...
;     ...
;         for (int ks = 0; ks < 12; ++ks) {
;           const bf16x8 kf = *(const bf16x8*)(cur + koff[ks & 3] + (ks >> 2) * 8192 + mt * 4096);
;           st[mt] = __builtin_amdgcn_mfma_f32_32x32x16_bf16(kf, qf[ks], st[mt], 0, 0, 0);
;         }
;       }
;       if (kt * 64 + 64 > nkeys) {
; #pragma unroll
;         for (int mt = 0; mt < 2; ++mt)
; #pragma unroll
;           for (int j = 0; j < 16; ++j) {
;             const int key = kt * 64 + mt * 32 + (j & 3) + 8 * (j >> 2) + 4 * h2;
;             if (key >= nkeys) st[mt][j] = -INFINITY;
;           }
;       }
;       float mx = fmaxf(st[0][0], st[1][0]);
; #pragma unroll
;       for (int j = 1; j < 16; ++j) mx = fmaxf(mx, fmaxf(st[0][j], st[1][j]));
;       mx = fmaxf(mx, __shfl_xor(mx, 32, 64));
;       const float m_new = fmaxf(m_run, mx);
;       const float alpha = __builtin_amdgcn_exp2f(m_run - m_new);
;       m_run = m_new;
;       float ps = 0.f;
; #pragma unroll
;       for (int mt = 0; mt < 2; ++mt)
; #pragma unroll
;         for (int j = 0; j < 16; ++j) { const float pv = __builtin_amdgcn_exp2f(st[mt][j] - m_new); st[mt][j] = pv; ps += pv; }
;       l_run = l_run * alpha + ps;
;       if (__any(alpha != 1.f)) {
; #pragma unroll
;         for (int i = 0; i < 4; ++i)
; #pragma unroll
;           for (int j = 0; j < 16; ++j) oacc[i][j] *= alpha;
;       }
	v_mfma_f32_32x32x16_bf16 v[80:95], v[158:161], v[124:127], v[80:95]
	ds_read_b128 v[158:161], v162 offset:12288
	s_waitcnt lgkmcnt(0)
	v_mfma_f32_32x32x16_bf16 v[80:95], v[158:161], v[120:123], v[80:95]
	ds_read_b128 v[158:161], v163 offset:12288
	s_waitcnt lgkmcnt(0)
	v_mfma_f32_32x32x16_bf16 v[80:95], v[158:161], v[116:119], v[80:95]
	ds_read_b128 v[158:161], v164 offset:12288
	s_waitcnt lgkmcnt(0)
	v_mfma_f32_32x32x16_bf16 v[80:95], v[158:161], v[112:115], v[80:95]
	ds_read_b128 v[158:161], v157 offset:20480
	s_waitcnt lgkmcnt(0)
	v_mfma_f32_32x32x16_bf16 v[80:95], v[158:161], v[108:111], v[80:95]
	ds_read_b128 v[158:161], v162 offset:20480
	s_waitcnt lgkmcnt(0)
	v_mfma_f32_32x32x16_bf16 v[80:95], v[158:161], v[104:107], v[80:95]
	ds_read_b128 v[158:161], v163 offset:20480
	s_waitcnt lgkmcnt(0)
	v_mfma_f32_32x32x16_bf16 v[80:95], v[158:161], v[100:103], v[80:95]
	ds_read_b128 v[158:161], v164 offset:20480
	s_waitcnt lgkmcnt(0)
	v_mfma_f32_32x32x16_bf16 v[80:95], v[158:161], v[96:99], v[80:95]
	v_max_f32_e32 v158, v65, v65
	v_max_f32_e32 v159, v66, v66
	v_max_f32_e32 v160, v67, v67
	s_nop 8
	v_max_f32_e32 v157, v81, v81
	v_max_f32_e32 v157, v158, v157
	v_max_f32_e32 v158, v82, v82
	v_max_f32_e32 v158, v159, v158
	v_max_f32_e32 v159, v83, v83
	v_max3_f32 v157, v64, v80, v157
	v_max_f32_e32 v159, v160, v159
	v_max3_f32 v157, v157, v158, v159
	v_max_f32_e32 v158, v84, v84
	v_max_f32_e32 v159, v68, v68
	v_max_f32_e32 v158, v159, v158
	v_max_f32_e32 v159, v85, v85
	v_max_f32_e32 v160, v69, v69
	v_max_f32_e32 v159, v160, v159
	v_max3_f32 v157, v157, v158, v159
	v_max_f32_e32 v158, v86, v86
	v_max_f32_e32 v159, v70, v70
	v_max_f32_e32 v158, v159, v158
	v_max_f32_e32 v159, v87, v87
	v_max_f32_e32 v160, v71, v71
	v_max_f32_e32 v159, v160, v159
	v_max3_f32 v157, v157, v158, v159
	v_max_f32_e32 v158, v88, v88
	v_max_f32_e32 v159, v72, v72
	v_max_f32_e32 v158, v159, v158
	v_max_f32_e32 v159, v89, v89
	v_max_f32_e32 v160, v73, v73
	v_max_f32_e32 v159, v160, v159
	v_max3_f32 v157, v157, v158, v159
	v_max_f32_e32 v158, v90, v90
	v_max_f32_e32 v159, v74, v74
	v_max_f32_e32 v158, v159, v158
	v_max_f32_e32 v159, v91, v91
	v_max_f32_e32 v160, v75, v75
	v_max_f32_e32 v159, v160, v159
	v_max3_f32 v157, v157, v158, v159
	v_max_f32_e32 v158, v92, v92
	v_max_f32_e32 v159, v76, v76
	v_max_f32_e32 v158, v159, v158
	v_max_f32_e32 v159, v93, v93
	v_max_f32_e32 v160, v77, v77
	v_max_f32_e32 v159, v160, v159
	v_max3_f32 v157, v157, v158, v159
	v_max_f32_e32 v158, v94, v94
	v_max_f32_e32 v159, v78, v78
	v_max_f32_e32 v158, v159, v158
	v_max_f32_e32 v159, v95, v95
	v_max_f32_e32 v160, v79, v79
	v_max_f32_e32 v159, v160, v159
	v_max3_f32 v157, v157, v158, v159
	v_cndmask_b32_e32 v158, v204, v206, vcc
	v_lshlrev_b32_e32 v158, 2, v158
	ds_bpermute_b32 v158, v158, v157
	s_waitcnt lgkmcnt(0)
	v_max3_f32 v157, v146, v157, v158
	v_sub_f32_e32 v146, v146, v157
	v_exp_f32_e32 v146, v146
	s_nop 0
	v_cmp_neq_f32_e32 vcc, 1.0, v146
	s_cbranch_vccz .LBB0_49
	v_pk_mul_f32 v[62:63], v[62:63], v[146:147] op_sel_hi:[1,0]
	v_pk_mul_f32 v[60:61], v[60:61], v[146:147] op_sel_hi:[1,0]
	v_pk_mul_f32 v[58:59], v[58:59], v[146:147] op_sel_hi:[1,0]
	v_pk_mul_f32 v[56:57], v[56:57], v[146:147] op_sel_hi:[1,0]
	v_pk_mul_f32 v[54:55], v[54:55], v[146:147] op_sel_hi:[1,0]
	v_pk_mul_f32 v[52:53], v[52:53], v[146:147] op_sel_hi:[1,0]
	v_pk_mul_f32 v[50:51], v[50:51], v[146:147] op_sel_hi:[1,0]
	v_pk_mul_f32 v[48:49], v[48:49], v[146:147] op_sel_hi:[1,0]
	v_pk_mul_f32 v[46:47], v[46:47], v[146:147] op_sel_hi:[1,0]
	v_pk_mul_f32 v[44:45], v[44:45], v[146:147] op_sel_hi:[1,0]
	v_pk_mul_f32 v[42:43], v[42:43], v[146:147] op_sel_hi:[1,0]
	v_pk_mul_f32 v[40:41], v[40:41], v[146:147] op_sel_hi:[1,0]
	v_pk_mul_f32 v[38:39], v[38:39], v[146:147] op_sel_hi:[1,0]
	v_pk_mul_f32 v[36:37], v[36:37], v[146:147] op_sel_hi:[1,0]
	v_pk_mul_f32 v[34:35], v[34:35], v[146:147] op_sel_hi:[1,0]
	v_pk_mul_f32 v[32:33], v[32:33], v[146:147] op_sel_hi:[1,0]
	v_pk_mul_f32 v[30:31], v[30:31], v[146:147] op_sel_hi:[1,0]
	v_pk_mul_f32 v[28:29], v[28:29], v[146:147] op_sel_hi:[1,0]
	v_pk_mul_f32 v[26:27], v[26:27], v[146:147] op_sel_hi:[1,0]
	v_pk_mul_f32 v[24:25], v[24:25], v[146:147] op_sel_hi:[1,0]
	v_pk_mul_f32 v[22:23], v[22:23], v[146:147] op_sel_hi:[1,0]
	v_pk_mul_f32 v[20:21], v[20:21], v[146:147] op_sel_hi:[1,0]
	v_pk_mul_f32 v[18:19], v[18:19], v[146:147] op_sel_hi:[1,0]
	v_pk_mul_f32 v[16:17], v[16:17], v[146:147] op_sel_hi:[1,0]
	v_pk_mul_f32 v[14:15], v[14:15], v[146:147] op_sel_hi:[1,0]
	v_pk_mul_f32 v[12:13], v[12:13], v[146:147] op_sel_hi:[1,0]
	v_pk_mul_f32 v[10:11], v[10:11], v[146:147] op_sel_hi:[1,0]
	v_pk_mul_f32 v[8:9], v[8:9], v[146:147] op_sel_hi:[1,0]
	v_pk_mul_f32 v[6:7], v[6:7], v[146:147] op_sel_hi:[1,0]
	v_pk_mul_f32 v[4:5], v[4:5], v[146:147] op_sel_hi:[1,0]
	v_pk_mul_f32 v[2:3], v[2:3], v[146:147] op_sel_hi:[1,0]
	v_pk_mul_f32 v[0:1], v[0:1], v[146:147] op_sel_hi:[1,0]

; DI void attn_item(const u16* __restrict__ qbuf, const u16* __restrict__ knope, const u16* __restrict__ krope, ...
;     ...
;     if (active && kt < my_tiles) {
;       const char* cur = smem + (kt & 1) * 40960;
;       f32x16 st[2];
; #pragma unroll
;       for (int mt = 0; mt < 2; ++mt) {
; #pragma unroll
;         for (int j = 0; j < 16; ++j) st[mt][j] = 0.f;
; #pragma unroll
;         for (int ks = 0; ks < 12; ++ks) {
;           const bf16x8 kf = *(const bf16x8*)(cur + koff[ks & 3] + (ks >> 2) * 8192 + mt * 4096);
;           st[mt] = __builtin_amdgcn_mfma_f32_32x32x16_bf16(kf, qf[ks], st[mt], 0, 0, 0);
;         }
;       }
;       if (kt * 64 + 64 > nkeys) {
; #pragma unroll
;         for (int mt = 0; mt < 2; ++mt)
; #pragma unroll
;           for (int j = 0; j < 16; ++j) {
;             const int key = kt * 64 + mt * 32 + (j & 3) + 8 * (j >> 2) + 4 * h2;
;             if (key >= nkeys) st[mt][j] = -INFINITY;
;           }
;       }
.LBB0_68:
	s_bitcmp1_b32 s17, 0
	s_cselect_b32 s17, 0xa000, 0
	v_or_b32_e32 v165, s17, v149
	v_or_b32_e32 v170, s17, v150
	v_or_b32_e32 v171, s17, v151
	v_or_b32_e32 v172, s17, v152
	ds_read_b128 v[224:227], v165
	ds_read_b128 v[228:231], v170
	ds_read_b128 v[232:235], v171
	ds_read_b128 v[236:239], v172
	ds_read_b128 v[240:243], v165 offset:8192
	ds_read_b128 v[244:247], v170 offset:8192
	ds_read_b128 v[248:251], v171 offset:8192
	ds_read_b128 v[186:189], v172 offset:8192
	s_waitcnt lgkmcnt(7)
	v_mfma_f32_32x32x16_bf16 v[64:79], v[224:227], v[140:143], 0
	ds_read_b128 v[224:227], v165 offset:16384
	s_waitcnt lgkmcnt(7)
	v_mfma_f32_32x32x16_bf16 v[64:79], v[228:231], v[136:139], v[64:79]
	ds_read_b128 v[228:231], v170 offset:16384
	s_waitcnt lgkmcnt(7)
	v_mfma_f32_32x32x16_bf16 v[64:79], v[232:235], v[132:135], v[64:79]
	ds_read_b128 v[232:235], v171 offset:16384
	s_waitcnt lgkmcnt(7)
	v_mfma_f32_32x32x16_bf16 v[64:79], v[236:239], v[128:131], v[64:79]
	ds_read_b128 v[236:239], v172 offset:16384
	s_waitcnt lgkmcnt(7)
	v_mfma_f32_32x32x16_bf16 v[64:79], v[240:243], v[124:127], v[64:79]
	ds_read_b128 v[240:243], v165 offset:4096
	s_waitcnt lgkmcnt(7)
	v_mfma_f32_32x32x16_bf16 v[64:79], v[244:247], v[120:123], v[64:79]
	ds_read_b128 v[244:247], v170 offset:4096
	s_waitcnt lgkmcnt(7)
	v_mfma_f32_32x32x16_bf16 v[64:79], v[248:251], v[116:119], v[64:79]
	ds_read_b128 v[248:251], v171 offset:4096
	s_waitcnt lgkmcnt(7)
	v_mfma_f32_32x32x16_bf16 v[64:79], v[186:189], v[112:115], v[64:79]
	ds_read_b128 v[186:189], v172 offset:4096
	s_waitcnt lgkmcnt(7)
	v_mfma_f32_32x32x16_bf16 v[64:79], v[224:227], v[108:111], v[64:79]
	ds_read_b128 v[224:227], v165 offset:12288
	s_waitcnt lgkmcnt(7)
	v_mfma_f32_32x32x16_bf16 v[64:79], v[228:231], v[104:107], v[64:79]
	ds_read_b128 v[228:231], v170 offset:12288
	s_waitcnt lgkmcnt(7)
	v_mfma_f32_32x32x16_bf16 v[64:79], v[232:235], v[100:103], v[64:79]
	ds_read_b128 v[232:235], v171 offset:12288
	s_waitcnt lgkmcnt(7)
	v_mfma_f32_32x32x16_bf16 v[64:79], v[236:239], v[96:99], v[64:79]
	ds_read_b128 v[236:239], v172 offset:12288
	s_waitcnt lgkmcnt(7)
	v_mfma_f32_32x32x16_bf16 v[80:95], v[240:243], v[140:143], 0
	ds_read_b128 v[240:243], v165 offset:20480
	s_waitcnt lgkmcnt(7)
	v_mfma_f32_32x32x16_bf16 v[80:95], v[244:247], v[136:139], v[80:95]
	ds_read_b128 v[244:247], v170 offset:20480
	s_waitcnt lgkmcnt(7)
	v_mfma_f32_32x32x16_bf16 v[80:95], v[248:251], v[132:135], v[80:95]
	ds_read_b128 v[248:251], v171 offset:20480
	s_waitcnt lgkmcnt(7)
	v_mfma_f32_32x32x16_bf16 v[80:95], v[186:189], v[128:131], v[80:95]
	ds_read_b128 v[186:189], v172 offset:20480
	s_waitcnt lgkmcnt(7)
	v_mfma_f32_32x32x16_bf16 v[80:95], v[224:227], v[124:127], v[80:95]
	ds_read_b128 v[224:227], v165 offset:24576
	s_waitcnt lgkmcnt(7)
	v_mfma_f32_32x32x16_bf16 v[80:95], v[228:231], v[120:123], v[80:95]
	ds_read_b128 v[228:231], v165 offset:28672
	s_waitcnt lgkmcnt(7)
	v_mfma_f32_32x32x16_bf16 v[80:95], v[232:235], v[116:119], v[80:95]
	ds_read_b128 v[232:235], v165 offset:32768
	s_waitcnt lgkmcnt(7)
	v_mfma_f32_32x32x16_bf16 v[80:95], v[236:239], v[112:115], v[80:95]
	ds_read_b128 v[236:239], v165 offset:36864
	s_waitcnt lgkmcnt(7)
	v_mfma_f32_32x32x16_bf16 v[80:95], v[240:243], v[108:111], v[80:95]
	ds_read_b128 v[240:243], v170 offset:24576
	s_waitcnt lgkmcnt(7)
	v_mfma_f32_32x32x16_bf16 v[80:95], v[244:247], v[104:107], v[80:95]
	ds_read_b128 v[244:247], v170 offset:28672
	s_waitcnt lgkmcnt(7)
	v_mfma_f32_32x32x16_bf16 v[80:95], v[248:251], v[100:103], v[80:95]
	ds_read_b128 v[248:251], v170 offset:32768
	s_waitcnt lgkmcnt(7)
	v_mfma_f32_32x32x16_bf16 v[80:95], v[186:189], v[96:99], v[80:95]
	ds_read_b128 v[186:189], v170 offset:36864
	s_cmp_lt_i32 s15, s14
	s_cbranch_scc1 .LBB0_70
	v_add_u32_e32 v165, s15, v156
	v_add_u32_e32 v166, 1, v165
	v_cmp_gt_i32_e32 vcc, s14, v165
	v_cmp_gt_i32_e64 s[40:41], s14, v166
	s_or_b64 vcc, s[40:41], vcc
	v_add_u32_e32 v166, 2, v165
	v_cndmask_b32_e32 v64, v212, v64, vcc
	v_cmp_gt_i32_e32 vcc, s14, v166
	v_add_u32_e32 v166, 3, v165
	v_cndmask_b32_e64 v65, v212, v65, s[40:41]
	v_cndmask_b32_e32 v66, v212, v66, vcc
	v_cmp_gt_i32_e32 vcc, s14, v166
	v_add_u32_e32 v166, 8, v165
	s_nop 0
	v_cndmask_b32_e32 v67, v212, v67, vcc
	v_cmp_gt_i32_e32 vcc, s14, v166
	v_add_u32_e32 v166, 9, v165
	s_nop 0
	v_cndmask_b32_e32 v68, v212, v68, vcc
	v_cmp_gt_i32_e32 vcc, s14, v166
	v_add_u32_e32 v166, 10, v165
	s_nop 0
	v_cndmask_b32_e32 v69, v212, v69, vcc
	v_cmp_gt_i32_e32 vcc, s14, v166
	v_add_u32_e32 v166, 11, v165
	s_nop 0
	v_cndmask_b32_e32 v70, v212, v70, vcc
	v_cmp_gt_i32_e32 vcc, s14, v166
	v_add_u32_e32 v166, 16, v165
	s_nop 0
	v_cndmask_b32_e32 v71, v212, v71, vcc
	v_cmp_gt_i32_e32 vcc, s14, v166
	v_add_u32_e32 v166, 17, v165
	s_nop 0
	v_cndmask_b32_e32 v72, v212, v72, vcc
	v_cmp_gt_i32_e32 vcc, s14, v166
	v_add_u32_e32 v166, 18, v165
	s_nop 0
	v_cndmask_b32_e32 v73, v212, v73, vcc
	v_cmp_gt_i32_e32 vcc, s14, v166
	v_add_u32_e32 v166, 19, v165
	s_nop 0
	v_cndmask_b32_e32 v74, v212, v74, vcc
	v_cmp_gt_i32_e32 vcc, s14, v166
	v_add_u32_e32 v166, 24, v165
	s_nop 0
	v_cndmask_b32_e32 v75, v212, v75, vcc
	v_cmp_gt_i32_e32 vcc, s14, v166
	v_add_u32_e32 v166, 25, v165
	s_nop 0
	v_cndmask_b32_e32 v76, v212, v76, vcc
	v_cmp_gt_i32_e32 vcc, s14, v166
	v_add_u32_e32 v166, 26, v165
	s_nop 0
	v_cndmask_b32_e32 v77, v212, v77, vcc
	v_cmp_gt_i32_e32 vcc, s14, v166
	v_add_u32_e32 v166, 27, v165
	s_nop 0
	v_cndmask_b32_e32 v78, v212, v78, vcc
	v_cmp_gt_i32_e32 vcc, s14, v166
	v_add_u32_e32 v166, 32, v165
	v_cmp_gt_i32_e64 s[40:41], s14, v166
	v_add_u32_e32 v166, 33, v165
	v_cmp_gt_i32_e64 s[42:43], s14, v166
	v_add_u32_e32 v166, 34, v165
; DI void attn_item(const u16* __restrict__ qbuf, const u16* __restrict__ knope, const u16* __restrict__ krope, ...
;     ...
;       if (kt * 64 + 64 > nkeys) {
; #pragma unroll
;         for (int mt = 0; mt < 2; ++mt)
; #pragma unroll
;           for (int j = 0; j < 16; ++j) {
;             const int key = kt * 64 + mt * 32 + (j & 3) + 8 * (j >> 2) + 4 * h2;
;             if (key >= nkeys) st[mt][j] = -INFINITY;
;           }
;       }
;       float mx = fmaxf(st[0][0], st[1][0]);
; #pragma unroll
;       for (int j = 1; j < 16; ++j) mx = fmaxf(mx, fmaxf(st[0][j], st[1][j]));
;       mx = fmaxf(mx, __shfl_xor(mx, 32, 64));
;       const float m_new = fmaxf(m_run, mx);
;       const float alpha = __builtin_amdgcn_exp2f(m_run - m_new);
;       m_run = m_new;
;       float ps = 0.f;
; #pragma unroll
;       for (int mt = 0; mt < 2; ++mt)
; #pragma unroll
;         for (int j = 0; j < 16; ++j) { const float pv = __builtin_amdgcn_exp2f(st[mt][j] - m_new); st[mt][j] = pv; ps += pv; }
;       l_run = l_run * alpha + ps;
;       if (__any(alpha != 1.f)) {
; #pragma unroll
;         for (int i = 0; i < 4; ++i)
; #pragma unroll
;           for (int j = 0; j < 16; ++j) oacc[i][j] *= alpha;
;       }
	v_cmp_gt_i32_e64 s[44:45], s14, v166
	v_add_u32_e32 v166, 35, v165
	v_cmp_gt_i32_e64 s[46:47], s14, v166
	v_add_u32_e32 v166, 40, v165
	v_cmp_gt_i32_e64 s[48:49], s14, v166
	v_add_u32_e32 v166, 41, v165
	v_cmp_gt_i32_e64 s[50:51], s14, v166
	v_add_u32_e32 v166, 42, v165
	v_cmp_gt_i32_e64 s[52:53], s14, v166
	v_add_u32_e32 v166, 43, v165
	v_cmp_gt_i32_e64 s[56:57], s14, v166
	v_add_u32_e32 v166, 48, v165
	v_cmp_gt_i32_e64 s[58:59], s14, v166
	v_add_u32_e32 v166, 49, v165
	v_cmp_gt_i32_e64 s[60:61], s14, v166
	v_add_u32_e32 v166, 50, v165
	v_cmp_gt_i32_e64 s[62:63], s14, v166
	v_add_u32_e32 v166, 51, v165
	v_cmp_gt_i32_e64 s[64:65], s14, v166
	v_add_u32_e32 v166, 56, v165
	v_cmp_gt_i32_e64 s[66:67], s14, v166
	v_add_u32_e32 v166, 57, v165
	v_cmp_gt_i32_e64 s[68:69], s14, v166
	v_add_u32_e32 v166, 58, v165
	v_add_u32_e32 v165, 59, v165
	v_cmp_gt_i32_e64 s[70:71], s14, v166
	v_cmp_gt_i32_e64 s[72:73], s14, v165
	s_or_b64 s[70:71], s[72:73], s[70:71]
	s_or_b64 s[68:69], s[70:71], s[68:69]
	s_or_b64 s[66:67], s[68:69], s[66:67]
	s_or_b64 s[64:65], s[66:67], s[64:65]
	s_or_b64 s[62:63], s[64:65], s[62:63]
	s_or_b64 s[60:61], s[62:63], s[60:61]
	s_or_b64 s[58:59], s[60:61], s[58:59]
	s_or_b64 s[56:57], s[58:59], s[56:57]
	s_or_b64 s[52:53], s[56:57], s[52:53]
	s_or_b64 s[50:51], s[52:53], s[50:51]
	s_or_b64 s[48:49], s[50:51], s[48:49]
	s_or_b64 s[46:47], s[48:49], s[46:47]
	s_or_b64 s[44:45], s[46:47], s[44:45]
	s_or_b64 s[42:43], s[44:45], s[42:43]
	s_or_b64 s[40:41], s[42:43], s[40:41]
	s_or_b64 vcc, s[40:41], vcc
	v_cndmask_b32_e64 v95, v212, v95, s[72:73]
	v_cndmask_b32_e64 v94, v212, v94, s[70:71]
	s_mov_b64 s[70:71], s[26:27]
	v_cndmask_b32_e64 v93, v212, v93, s[68:69]
	s_mov_b64 s[68:69], s[24:25]
	v_cndmask_b32_e64 v92, v212, v92, s[66:67]
	s_mov_b64 s[66:67], 0x5a8080
	v_cndmask_b32_e64 v91, v212, v91, s[64:65]
	s_mov_b32 s65, 0x2aaaaaab
	s_movk_i32 s64, 0x41ff
	v_cndmask_b32_e64 v90, v212, v90, s[62:63]
	v_cndmask_b32_e64 v89, v212, v89, s[60:61]
	v_cndmask_b32_e64 v88, v212, v88, s[58:59]
	v_cndmask_b32_e64 v87, v212, v87, s[56:57]
	v_cndmask_b32_e64 v86, v212, v86, s[52:53]
	v_cndmask_b32_e64 v85, v212, v85, s[50:51]
	v_cndmask_b32_e64 v84, v212, v84, s[48:49]
	v_cndmask_b32_e64 v83, v212, v83, s[46:47]
	v_cndmask_b32_e64 v82, v212, v82, s[44:45]
	v_cndmask_b32_e64 v81, v212, v81, s[42:43]
	v_cndmask_b32_e64 v80, v212, v80, s[40:41]
	v_cndmask_b32_e32 v79, v212, v79, vcc
.LBB0_70:
	v_max3_f32 v166, v64, v65, v66
	v_max3_f32 v167, v67, v68, v69
	v_max3_f32 v166, v166, v70, v71
	v_max3_f32 v167, v167, v72, v73
	v_max3_f32 v166, v166, v74, v75
	v_max3_f32 v167, v167, v76, v77
	v_max3_f32 v166, v166, v78, v79
	v_max_f32_e32 v166, v166, v167
	s_nop 1
	v_max3_f32 v167, v80, v81, v82
	v_max3_f32 v168, v83, v84, v85
	v_max3_f32 v167, v167, v86, v87
	v_max3_f32 v168, v168, v88, v89
	v_max3_f32 v167, v167, v90, v91
	v_max3_f32 v168, v168, v92, v93
	v_max3_f32 v167, v167, v94, v95
	v_max3_f32 v166, v166, v167, v168
	v_mov_b32_e32 v167, v166
	s_nop 1
	v_permlane32_swap_b32_e32 v166, v167
	v_max3_f32 v165, v146, v166, v167
	v_sub_f32_e32 v146, v146, v165
	v_exp_f32_e32 v146, v146
	s_nop 0
	v_cmp_neq_f32_e32 vcc, 1.0, v146
	s_cbranch_vccz .LBB0_72
	v_pk_mul_f32 v[62:63], v[62:63], v[146:147] op_sel_hi:[1,0]
	v_pk_mul_f32 v[60:61], v[60:61], v[146:147] op_sel_hi:[1,0]
	v_pk_mul_f32 v[58:59], v[58:59], v[146:147] op_sel_hi:[1,0]
	v_pk_mul_f32 v[56:57], v[56:57], v[146:147] op_sel_hi:[1,0]
	v_pk_mul_f32 v[54:55], v[54:55], v[146:147] op_sel_hi:[1,0]
	v_pk_mul_f32 v[52:53], v[52:53], v[146:147] op_sel_hi:[1,0]
	v_pk_mul_f32 v[50:51], v[50:51], v[146:147] op_sel_hi:[1,0]
	v_pk_mul_f32 v[48:49], v[48:49], v[146:147] op_sel_hi:[1,0]
	v_pk_mul_f32 v[46:47], v[46:47], v[146:147] op_sel_hi:[1,0]
	v_pk_mul_f32 v[44:45], v[44:45], v[146:147] op_sel_hi:[1,0]
	v_pk_mul_f32 v[42:43], v[42:43], v[146:147] op_sel_hi:[1,0]
	v_pk_mul_f32 v[40:41], v[40:41], v[146:147] op_sel_hi:[1,0]
	v_pk_mul_f32 v[38:39], v[38:39], v[146:147] op_sel_hi:[1,0]
	v_pk_mul_f32 v[36:37], v[36:37], v[146:147] op_sel_hi:[1,0]
	v_pk_mul_f32 v[34:35], v[34:35], v[146:147] op_sel_hi:[1,0]
	v_pk_mul_f32 v[32:33], v[32:33], v[146:147] op_sel_hi:[1,0]
	v_pk_mul_f32 v[30:31], v[30:31], v[146:147] op_sel_hi:[1,0]
	v_pk_mul_f32 v[28:29], v[28:29], v[146:147] op_sel_hi:[1,0]
	v_pk_mul_f32 v[26:27], v[26:27], v[146:147] op_sel_hi:[1,0]
	v_pk_mul_f32 v[24:25], v[24:25], v[146:147] op_sel_hi:[1,0]
	v_pk_mul_f32 v[22:23], v[22:23], v[146:147] op_sel_hi:[1,0]
	v_pk_mul_f32 v[20:21], v[20:21], v[146:147] op_sel_hi:[1,0]
	v_pk_mul_f32 v[18:19], v[18:19], v[146:147] op_sel_hi:[1,0]
	v_pk_mul_f32 v[16:17], v[16:17], v[146:147] op_sel_hi:[1,0]
	v_pk_mul_f32 v[14:15], v[14:15], v[146:147] op_sel_hi:[1,0]
	v_pk_mul_f32 v[12:13], v[12:13], v[146:147] op_sel_hi:[1,0]
	v_pk_mul_f32 v[10:11], v[10:11], v[146:147] op_sel_hi:[1,0]
	v_pk_mul_f32 v[8:9], v[8:9], v[146:147] op_sel_hi:[1,0]
	v_pk_mul_f32 v[6:7], v[6:7], v[146:147] op_sel_hi:[1,0]
	v_pk_mul_f32 v[4:5], v[4:5], v[146:147] op_sel_hi:[1,0]
	v_pk_mul_f32 v[2:3], v[2:3], v[146:147] op_sel_hi:[1,0]
	v_pk_mul_f32 v[0:1], v[0:1], v[146:147] op_sel_hi:[1,0]
; DI unsigned pk2(float a, float b) { f32x2_t f = {a, b}; return __builtin_bit_cast(unsigned, __builtin_convertvector(f, bf16x2_t)); }
; DI void attn_item(const u16* __restrict__ qbuf, const u16* __restrict__ knope, const u16* __restrict__ krope, ...
;     ...
;       float ps = 0.f;
; #pragma unroll
;       for (int mt = 0; mt < 2; ++mt)
; #pragma unroll
;         for (int j = 0; j < 16; ++j) { const float pv = __builtin_amdgcn_exp2f(st[mt][j] - m_new); st[mt][j] = pv; ps += pv; }
;       l_run = l_run * alpha + ps;
;       if (__any(alpha != 1.f)) {
; #pragma unroll
;         for (int i = 0; i < 4; ++i)
; #pragma unroll
;           for (int j = 0; j < 16; ++j) oacc[i][j] *= alpha;
;       }
; #pragma unroll
;       for (int mt = 0; mt < 2; ++mt)
; #pragma unroll
;         for (int s = 0; s < 2; ++s) {
;           union { bf16x8 v; unsigned u[4]; } pf;
; #pragma unroll
;           for (int k = 0; k < 4; ++k) pf.u[k] = pk2(st[mt][8 * s + 2 * k], st[mt][8 * s + 2 * k + 1]);
; #pragma unroll
;           for (int vt4 = 0; vt4 < 4; ++vt4) {
;             const bf16x8 vf = *(const bf16x8*)(cur + 24576 + koff[mt * 2 + s] + vt4 * 4096);
;             oacc[vt4] = __builtin_amdgcn_mfma_f32_32x32x16_bf16(vf, pf.v, oacc[vt4], 0, 0, 0);
;           }
;         }
.LBB0_72:
	v_sub_f32_e32 v64, v64, v165
	v_sub_f32_e32 v65, v65, v165
	v_sub_f32_e32 v66, v66, v165
	v_sub_f32_e32 v67, v67, v165
	v_sub_f32_e32 v68, v68, v165
	v_sub_f32_e32 v69, v69, v165
	v_sub_f32_e32 v70, v70, v165
	v_sub_f32_e32 v71, v71, v165
	v_exp_f32_e32 v64, v64
	v_exp_f32_e32 v65, v65
	v_exp_f32_e32 v66, v66
	v_exp_f32_e32 v67, v67
	v_exp_f32_e32 v68, v68
	v_exp_f32_e32 v69, v69
	v_exp_f32_e32 v70, v70
	v_exp_f32_e32 v71, v71
	v_add_f32_e32 v166, v64, v65
	v_add_f32_e32 v167, v66, v67
	v_add_f32_e32 v166, v166, v68
	v_add_f32_e32 v167, v167, v69
	v_add_f32_e32 v166, v166, v70
	v_add_f32_e32 v167, v167, v71
	v_cvt_pk_bf16_f32 v64, v64, v65
	v_cvt_pk_bf16_f32 v65, v66, v67
	v_cvt_pk_bf16_f32 v66, v68, v69
	v_cvt_pk_bf16_f32 v67, v70, v71
	v_add_f32_e32 v168, v166, v167
	v_nop
	s_waitcnt lgkmcnt(7)
	v_mfma_f32_32x32x16_bf16 v[48:63], v[224:227], v[64:67], v[48:63]
	ds_read_b128 v[224:227], v171 offset:24576
	v_sub_f32_e32 v72, v72, v165
	v_sub_f32_e32 v73, v73, v165
	v_sub_f32_e32 v74, v74, v165
	v_sub_f32_e32 v75, v75, v165
	v_sub_f32_e32 v76, v76, v165
	v_sub_f32_e32 v77, v77, v165
	v_sub_f32_e32 v78, v78, v165
	s_waitcnt lgkmcnt(7)
	v_mfma_f32_32x32x16_bf16 v[32:47], v[228:231], v[64:67], v[32:47]
	ds_read_b128 v[228:231], v171 offset:28672
	v_sub_f32_e32 v79, v79, v165
	v_exp_f32_e32 v72, v72
	v_exp_f32_e32 v73, v73
	v_exp_f32_e32 v74, v74
	v_exp_f32_e32 v75, v75
	v_exp_f32_e32 v76, v76
	v_exp_f32_e32 v77, v77
	s_waitcnt lgkmcnt(7)
	v_mfma_f32_32x32x16_bf16 v[16:31], v[232:235], v[64:67], v[16:31]
	ds_read_b128 v[232:235], v171 offset:32768
	v_exp_f32_e32 v78, v78
	v_exp_f32_e32 v79, v79
	v_add_f32_e32 v166, v72, v73
	v_add_f32_e32 v167, v74, v75
	v_add_f32_e32 v166, v166, v76
	v_add_f32_e32 v167, v167, v77
	v_add_f32_e32 v166, v166, v78
	s_waitcnt lgkmcnt(7)
	v_mfma_f32_32x32x16_bf16 v[0:15], v[236:239], v[64:67], v[0:15]
	ds_read_b128 v[236:239], v171 offset:36864
	v_add_f32_e32 v167, v167, v79
	v_cvt_pk_bf16_f32 v72, v72, v73
	v_cvt_pk_bf16_f32 v73, v74, v75
	v_cvt_pk_bf16_f32 v74, v76, v77
	v_cvt_pk_bf16_f32 v75, v78, v79
	v_add_f32_e32 v168, v168, v166
	v_add_f32_e32 v168, v168, v167
	s_waitcnt lgkmcnt(7)
	v_mfma_f32_32x32x16_bf16 v[48:63], v[240:243], v[72:75], v[48:63]
	ds_read_b128 v[240:243], v172 offset:24576
	v_sub_f32_e32 v80, v80, v165
	v_sub_f32_e32 v81, v81, v165
	v_sub_f32_e32 v82, v82, v165
	v_sub_f32_e32 v83, v83, v165
	v_sub_f32_e32 v84, v84, v165
	v_sub_f32_e32 v85, v85, v165
	v_sub_f32_e32 v86, v86, v165
	s_waitcnt lgkmcnt(7)
	v_mfma_f32_32x32x16_bf16 v[32:47], v[244:247], v[72:75], v[32:47]
	ds_read_b128 v[244:247], v172 offset:28672
	v_sub_f32_e32 v87, v87, v165
	v_exp_f32_e32 v80, v80
	v_exp_f32_e32 v81, v81
	v_exp_f32_e32 v82, v82
	v_exp_f32_e32 v83, v83
	v_exp_f32_e32 v84, v84
	v_exp_f32_e32 v85, v85
	s_waitcnt lgkmcnt(7)
	v_mfma_f32_32x32x16_bf16 v[16:31], v[248:251], v[72:75], v[16:31]
	ds_read_b128 v[248:251], v172 offset:32768
	v_exp_f32_e32 v86, v86
	v_exp_f32_e32 v87, v87
	v_add_f32_e32 v166, v80, v81
	v_add_f32_e32 v167, v82, v83
	v_add_f32_e32 v166, v166, v84
	v_add_f32_e32 v167, v167, v85
	v_add_f32_e32 v166, v166, v86
	s_waitcnt lgkmcnt(7)
	v_mfma_f32_32x32x16_bf16 v[0:15], v[186:189], v[72:75], v[0:15]
	ds_read_b128 v[186:189], v172 offset:36864
	v_add_f32_e32 v167, v167, v87
	v_cvt_pk_bf16_f32 v80, v80, v81
	v_cvt_pk_bf16_f32 v81, v82, v83
	v_cvt_pk_bf16_f32 v82, v84, v85
	v_cvt_pk_bf16_f32 v83, v86, v87
	v_add_f32_e32 v168, v168, v166
	v_add_f32_e32 v168, v168, v167
	s_waitcnt lgkmcnt(7)
	v_mfma_f32_32x32x16_bf16 v[48:63], v[224:227], v[80:83], v[48:63]
	v_sub_f32_e32 v88, v88, v165
	v_sub_f32_e32 v89, v89, v165
	v_sub_f32_e32 v90, v90, v165
	v_sub_f32_e32 v91, v91, v165
	v_sub_f32_e32 v92, v92, v165
	v_sub_f32_e32 v93, v93, v165
	v_sub_f32_e32 v94, v94, v165
	s_waitcnt lgkmcnt(6)
	v_mfma_f32_32x32x16_bf16 v[32:47], v[228:231], v[80:83], v[32:47]
	v_sub_f32_e32 v95, v95, v165
	v_exp_f32_e32 v88, v88
	v_exp_f32_e32 v89, v89
	v_exp_f32_e32 v90, v90
	v_exp_f32_e32 v91, v91
	v_exp_f32_e32 v92, v92
	v_exp_f32_e32 v93, v93
	s_waitcnt lgkmcnt(5)
	v_mfma_f32_32x32x16_bf16 v[16:31], v[232:235], v[80:83], v[16:31]
	v_exp_f32_e32 v94, v94
	v_exp_f32_e32 v95, v95
	v_add_f32_e32 v166, v88, v89
	v_add_f32_e32 v167, v90, v91
	v_add_f32_e32 v166, v166, v92
	v_add_f32_e32 v167, v167, v93
	v_add_f32_e32 v166, v166, v94
	s_waitcnt lgkmcnt(4)
	v_mfma_f32_32x32x16_bf16 v[0:15], v[236:239], v[80:83], v[0:15]
	v_add_f32_e32 v167, v167, v95
	v_cvt_pk_bf16_f32 v88, v88, v89
	v_cvt_pk_bf16_f32 v89, v90, v91
	v_cvt_pk_bf16_f32 v90, v92, v93
	v_cvt_pk_bf16_f32 v91, v94, v95
	v_add_f32_e32 v168, v168, v166
	v_add_f32_e32 v168, v168, v167
	s_waitcnt lgkmcnt(3)
	v_mfma_f32_32x32x16_bf16 v[48:63], v[240:243], v[88:91], v[48:63]
	v_fmac_f32_e32 v168, v164, v146
	s_waitcnt lgkmcnt(2)
	v_mfma_f32_32x32x16_bf16 v[32:47], v[244:247], v[88:91], v[32:47]
	v_mov_b32_e32 v146, v165
	s_waitcnt lgkmcnt(1)
	v_mfma_f32_32x32x16_bf16 v[16:31], v[248:251], v[88:91], v[16:31]
	v_mov_b32_e32 v164, v168
	s_waitcnt lgkmcnt(0)
	v_mfma_f32_32x32x16_bf16 v[0:15], v[186:189], v[88:91], v[0:15]
	s_or_b64 exec, exec, s[84:85]
	s_add_i32 s15, s15, 64
	s_cmp_eq_u32 s13, s16
	s_cbranch_scc1 .LBB0_75

; DI int get_bid() { int b = blockIdx.x; asm volatile("" : "+s"(b)); return b; }
; DI void phase_even(const Params& p, int e, int sub, char* smem) {
;     ...
;     for (int t = get_bid(); t < 512 + 64; t += gridDim.x) {
;       if (t < 512) {
;         const int tm = t >> 3, tn = t & 7;
;         gemm_dma<256>(gbuf + (size_t)tm * 256 * 2048, 2048, W + WE_OUT + (size_t)tn * 128 * 2048, 2048, 2048, smem, tm * 256, tn * 128, epi);
;       } else {
;         const int u = t - 512, tm = u >> 3, tn = u & 7, m0 = M_PROMPT + tm * 64;
;         gemm_tile<2>(gbuf + (size_t)m0 * 2048, 2048, W + WE_OUT + (size_t)tn * 128 * 2048, 2048, 2048, smem, m0, tn * 128, epi);
;       }
;     }
.LBB0_282:
	s_and_b64 vcc, exec, s[38:39]
	s_cbranch_vccz .LBB0_294
	s_mov_b32 s4, s2
	v_readlane_b32 s98, v255, 11
	s_nop 0
	s_cmp_lg_u32 s98, 0x200
	s_cbranch_scc1 .Lxmap_skip2
	s_and_b32 s98, s4, 7
	s_lshl_b32 s98, s98, 6
	s_bfe_u32 s99, s4, 0x30006
	s_lshl_b32 s99, s99, 3
	s_or_b32 s98, s98, s99
	s_bfe_u32 s99, s4, 0x30003
	s_or_b32 s4, s98, s99
.Lxmap_skip2:
	s_cmpk_gt_i32 s4, 0x23f
	s_cbranch_scc1 .LBB0_294
	s_lshl_b32 s5, s4, 3
	s_mov_b32 s6, s4
	s_waitcnt vmcnt(0)
	s_branch .LBB0_286

; DI int get_bid() { int b = blockIdx.x; asm volatile("" : "+s"(b)); return b; }
; DI void phase_odd(const Params& p, int o, int sub, char* smem) {
;     ...
;   } else if (sub == 4) {
;     ...
;     attn_phase(p, smem, true);
;     ...
;     attn_phase(p, smem, false);
;   } else if (sub == 5) {
;     EpiBF16 epi{(u16*)(p.ws + OFF_KN), 1024};
;     const u16* ao = (const u16*)(p.ws + OFF_GO);
;     for (int t = get_bid(); t < 512 + 64; t += gridDim.x) {
;       if (t < 512) {
;         const int tm = t >> 3, tn = t & 7;
;         gemm_dma<256>(ao + (size_t)tm * 256 * 1024, 1024, W + WO_O + (size_t)tn * 128 * 1024, 1024, 1024, smem, tm * 256, tn * 128, epi);
;       } else {
;         const int u = t - 512, tm = u >> 3, tn = u & 7, m0 = M_PROMPT + tm * 64;
;         gemm_tile<2>(ao + (size_t)m0 * 1024, 1024, W + WO_O + (size_t)tn * 128 * 1024, 1024, 1024, smem, m0, tn * 128, epi);
;       }
;     }
.LBB0_1126:
	s_andn2_b64 vcc, exec, s[38:39]
	s_cbranch_vccnz .LBB0_1762
	v_readlane_b32 s4, v255, 27
	s_mov_b64 s[40:41], -1
	s_mov_b64 s[38:39], 0
	s_cmp_lt_i32 s4, 3
	s_mov_b64 s[82:83], 0
	s_cbranch_scc1 .LBB0_1160
	v_readlane_b32 s4, v255, 27
	s_cmp_gt_i32 s4, 3
	s_cbranch_scc0 .LBB0_1143
	s_cmp_eq_u32 s4, 4
	s_mov_b64 s[82:83], -1
	s_cbranch_scc0 .LBB0_1142
	s_mov_b32 s4, s2
	v_readlane_b32 s98, v255, 11
	s_nop 0
	s_cmp_lg_u32 s98, 0x200
	s_cbranch_scc1 .Lxmap_skip1
	s_and_b32 s98, s4, 7
	s_lshl_b32 s98, s98, 6
	s_bfe_u32 s99, s4, 0x30006
	s_lshl_b32 s99, s99, 3
	s_or_b32 s98, s98, s99
	s_bfe_u32 s99, s4, 0x30003
	s_or_b32 s4, s98, s99
.Lxmap_skip1:
	v_readlane_b32 s46, v254, 63
	v_readlane_b32 s48, v255, 1
	v_readlane_b32 s50, v255, 3
	v_readlane_b32 s52, v255, 13
	s_cmpk_gt_i32 s4, 0x23f
	v_readlane_b32 s44, v254, 56
	v_readlane_b32 s47, v255, 0
	v_readlane_b32 s49, v255, 2
	v_readlane_b32 s51, v255, 4
	v_readlane_b32 s53, v255, 14
	s_mov_b64 s[56:57], 0x8000
	s_mov_b64 s[58:59], 0x10000
	s_mov_b64 s[60:61], 0x18000
	s_mov_b64 s[62:63], 0x10040
	s_mov_b64 s[82:83], 0xa10080
	s_cbranch_scc1 .LBB0_1141
	s_lshl_b32 s5, s4, 3
	s_mov_b32 s6, s4
	s_waitcnt vmcnt(0)
	s_branch .LBB0_1133
.LBB0_1132:
	v_readlane_b32 s8, v255, 5
	v_readlane_b32 s14, v255, 11
	s_cmp_lg_u32 s14, 0x200
	s_cbranch_scc1 .Lxmap_lskip1
	s_cmpk_gt_i32 s6, 0x1ff
	s_cbranch_scc1 .Lxmap_lskip1
	s_mov_b32 s4, s2
	s_mov_b32 s6, s2
	s_lshl_b32 s5, s2, 3
.Lxmap_lskip1:
	s_add_i32 s6, s6, s14
	s_add_i32 s4, s4, s14
	s_add_i32 s5, s5, s44
	s_cmpk_gt_i32 s6, 0x23f
	v_readlane_b32 s9, v255, 6
	v_readlane_b32 s10, v255, 7
	v_readlane_b32 s11, v255, 8
	v_readlane_b32 s12, v255, 9
	v_readlane_b32 s13, v255, 10
	v_readlane_b32 s15, v255, 12
	s_cbranch_scc1 .LBB0_1141
